# P2: f32-MFMA block update in the WY solve; stage F: conversion ticket taken early, KDt LDS reads batched
# baseline (speedup 1.0000x reference)
.LBB0_360:
	s_or_b64 exec, exec, s[4:5]
	s_waitcnt lgkmcnt(0)
	s_barrier
	s_and_saveexec_b64 s[4:5], s[44:45]
	s_xor_b64 s[4:5], exec, s[4:5]
	s_cbranch_execz .LBB0_373
	s_mov_b64 s[6:7], exec
	s_and_b64 exec, exec, s[42:43]
	s_cbranch_execz .Ltk_skip
	v_mov_b32_e32 v254, 1
	v_mov_b32_e32 v253, 0
	v_readlane_b32 s10, v238, 21
	v_readlane_b32 s11, v238, 22
	s_nop 4
	global_atomic_add v254, v253, v254, s[10:11] sc0
.Ltk_skip:
	s_mov_b64 exec, s[6:7]
	ds_read_b32 v16, v131
	v_lshl_add_u64 v[0:1], s[96:97], 0, v[76:77]
	v_lshl_add_u64 v[18:19], v[0:1], 0, v[78:79]
	ds_read_b128 v[0:3], v183
	ds_read_b128 v[4:7], v183 offset:16
	ds_read_b128 v[8:11], v183 offset:32
	ds_read_b128 v[12:15], v183 offset:48
	s_mov_b64 s[6:7], 0x4400
	s_waitcnt lgkmcnt(3)
	v_lshlrev_b32_e32 v22, 16, v0
	v_and_b32_e32 v23, 0xffff0000, v0
	v_pk_mul_f32 v[22:23], v[16:17], v[22:23] op_sel_hi:[0,1]
	v_cvt_pk_bf16_f32 v0, v22, v23
	v_lshlrev_b32_e32 v22, 16, v1
	v_and_b32_e32 v23, 0xffff0000, v1
	v_pk_mul_f32 v[22:23], v[16:17], v[22:23] op_sel_hi:[0,1]
	v_cvt_pk_bf16_f32 v1, v22, v23
	v_lshlrev_b32_e32 v22, 16, v2
	v_and_b32_e32 v23, 0xffff0000, v2
	v_pk_mul_f32 v[22:23], v[16:17], v[22:23] op_sel_hi:[0,1]
	v_lshl_add_u64 v[20:21], v[18:19], 0, s[6:7]
	v_cvt_pk_bf16_f32 v2, v22, v23
	v_lshlrev_b32_e32 v22, 16, v3
	v_and_b32_e32 v23, 0xffff0000, v3
	s_movk_i32 s6, 0x4000
	v_pk_mul_f32 v[22:23], v[16:17], v[22:23] op_sel_hi:[0,1]
	v_add_co_u32_e32 v18, vcc, s6, v18
	v_cvt_pk_bf16_f32 v3, v22, v23
	s_nop 0
	v_addc_co_u32_e32 v19, vcc, 0, v19, vcc
	global_store_dwordx4 v[18:19], v[0:3], off offset:1024
	s_mov_b64 s[6:7], 0xac00
	s_waitcnt lgkmcnt(2)
	v_lshlrev_b32_e32 v0, 16, v4
	v_and_b32_e32 v1, 0xffff0000, v4
	v_lshlrev_b32_e32 v2, 16, v5
	v_and_b32_e32 v3, 0xffff0000, v5
	v_pk_mul_f32 v[0:1], v[16:17], v[0:1] op_sel_hi:[0,1]
	v_pk_mul_f32 v[2:3], v[16:17], v[2:3] op_sel_hi:[0,1]
	v_cvt_pk_bf16_f32 v0, v0, v1
	v_cvt_pk_bf16_f32 v1, v2, v3
	v_lshlrev_b32_e32 v2, 16, v6
	v_and_b32_e32 v3, 0xffff0000, v6
	v_lshlrev_b32_e32 v4, 16, v7
	v_and_b32_e32 v5, 0xffff0000, v7
	v_pk_mul_f32 v[2:3], v[16:17], v[2:3] op_sel_hi:[0,1]
	v_pk_mul_f32 v[4:5], v[16:17], v[4:5] op_sel_hi:[0,1]
	v_cvt_pk_bf16_f32 v2, v2, v3
	v_cvt_pk_bf16_f32 v3, v4, v5
	global_store_dwordx4 v[20:21], v[0:3], off offset:16
	s_waitcnt lgkmcnt(1)
	v_lshlrev_b32_e32 v4, 16, v11
	v_and_b32_e32 v5, 0xffff0000, v11
	v_lshlrev_b32_e32 v0, 16, v8
	v_and_b32_e32 v1, 0xffff0000, v8
	v_lshlrev_b32_e32 v2, 16, v9
	v_and_b32_e32 v3, 0xffff0000, v9
	v_pk_mul_f32 v[0:1], v[16:17], v[0:1] op_sel_hi:[0,1]
	v_pk_mul_f32 v[2:3], v[16:17], v[2:3] op_sel_hi:[0,1]
	v_cvt_pk_bf16_f32 v0, v0, v1
	v_cvt_pk_bf16_f32 v1, v2, v3
	v_lshlrev_b32_e32 v2, 16, v10
	v_and_b32_e32 v3, 0xffff0000, v10
	v_pk_mul_f32 v[2:3], v[16:17], v[2:3] op_sel_hi:[0,1]
	v_pk_mul_f32 v[4:5], v[16:17], v[4:5] op_sel_hi:[0,1]
	v_cvt_pk_bf16_f32 v2, v2, v3
	v_cvt_pk_bf16_f32 v3, v4, v5
	global_store_dwordx4 v[20:21], v[0:3], off offset:32
	s_waitcnt lgkmcnt(0)
	v_lshlrev_b32_e32 v4, 16, v15
	v_and_b32_e32 v5, 0xffff0000, v15
	v_lshlrev_b32_e32 v0, 16, v12
	v_and_b32_e32 v1, 0xffff0000, v12
	v_lshlrev_b32_e32 v2, 16, v13
	v_and_b32_e32 v3, 0xffff0000, v13
	v_pk_mul_f32 v[0:1], v[16:17], v[0:1] op_sel_hi:[0,1]
	v_pk_mul_f32 v[2:3], v[16:17], v[2:3] op_sel_hi:[0,1]
	v_cvt_pk_bf16_f32 v0, v0, v1
	v_cvt_pk_bf16_f32 v1, v2, v3
	v_lshlrev_b32_e32 v2, 16, v14
	v_and_b32_e32 v3, 0xffff0000, v14
	v_pk_mul_f32 v[2:3], v[16:17], v[2:3] op_sel_hi:[0,1]
	v_pk_mul_f32 v[4:5], v[16:17], v[4:5] op_sel_hi:[0,1]
	v_cvt_pk_bf16_f32 v2, v2, v3
	v_cvt_pk_bf16_f32 v3, v4, v5
	global_store_dwordx4 v[20:21], v[0:3], off offset:48
	s_nop 1
	v_lshl_add_u64 v[0:1], s[96:97], 0, v[82:83]
	v_lshl_add_u64 v[6:7], v[0:1], 0, v[84:85]
	v_lshl_add_u64 v[4:5], v[6:7], 0, s[6:7]
	s_mov_b32 s6, 0xa000
	v_add_co_u32_e32 v6, vcc, s6, v6
	s_nop 1
	v_addc_co_u32_e32 v7, vcc, 0, v7, vcc
	ds_read_u16 v240, v172
	ds_read_u16 v241, v172 offset:272
	ds_read_u16 v242, v173
	ds_read_u16 v243, v172 offset:816
	ds_read_u16 v244, v173 offset:544
	ds_read_u16 v245, v172 offset:1360
	ds_read_u16 v246, v173 offset:1088
	ds_read_u16 v247, v172 offset:1904
	ds_read_b128 v[248:251], v157
	ds_read_b128 v[20:23], v158
	s_waitcnt lgkmcnt(0)
	v_lshlrev_b32_e32 v8, 16, v240
	v_lshlrev_b32_e32 v9, 16, v241
	v_lshlrev_b32_e32 v10, 16, v242
	v_lshlrev_b32_e32 v11, 16, v243
	v_lshlrev_b32_e32 v12, 16, v244
	v_lshlrev_b32_e32 v13, 16, v245
	v_lshlrev_b32_e32 v14, 16, v246
	v_lshlrev_b32_e32 v15, 16, v247
	v_pk_mul_f32 v[8:9], v[248:249], v[8:9]
	v_pk_mul_f32 v[10:11], v[250:251], v[10:11]
	v_pk_mul_f32 v[12:13], v[20:21], v[12:13]
	v_pk_mul_f32 v[14:15], v[22:23], v[14:15]
	ds_read_u16 v240, v173 offset:1632
	ds_read_u16 v241, v172 offset:2448
	ds_read_u16 v242, v173 offset:2176
	ds_read_u16 v243, v172 offset:2992
	ds_read_u16 v244, v173 offset:2720
	ds_read_u16 v245, v172 offset:3536
	ds_read_u16 v246, v173 offset:3264
	ds_read_u16 v247, v172 offset:4080
	ds_read_b128 v[248:251], v159
	ds_read_b128 v[20:23], v160
	v_cvt_pk_bf16_f32 v0, v8, v9
	v_cvt_pk_bf16_f32 v1, v10, v11
	v_cvt_pk_bf16_f32 v2, v12, v13
	v_cvt_pk_bf16_f32 v3, v14, v15
	global_store_dwordx4 v[6:7], v[0:3], off offset:3072
	s_waitcnt lgkmcnt(0)
	v_lshlrev_b32_e32 v8, 16, v240
	v_lshlrev_b32_e32 v9, 16, v241
	v_lshlrev_b32_e32 v10, 16, v242
	v_lshlrev_b32_e32 v11, 16, v243
	v_lshlrev_b32_e32 v12, 16, v244
	v_lshlrev_b32_e32 v13, 16, v245
	v_lshlrev_b32_e32 v14, 16, v246
	v_lshlrev_b32_e32 v15, 16, v247
	v_pk_mul_f32 v[8:9], v[248:249], v[8:9]
	v_pk_mul_f32 v[10:11], v[250:251], v[10:11]
	v_pk_mul_f32 v[12:13], v[20:21], v[12:13]
	v_pk_mul_f32 v[14:15], v[22:23], v[14:15]
	ds_read_u16 v240, v173 offset:3808
	ds_read_u16 v241, v172 offset:4624
	ds_read_u16 v242, v173 offset:4352
	ds_read_u16 v243, v172 offset:5168
	ds_read_u16 v244, v173 offset:4896
	ds_read_u16 v245, v172 offset:5712
	ds_read_u16 v246, v173 offset:5440
	ds_read_u16 v247, v172 offset:6256
	ds_read_b128 v[248:251], v161
	ds_read_b128 v[20:23], v162
	v_cvt_pk_bf16_f32 v0, v8, v9
	v_cvt_pk_bf16_f32 v1, v10, v11
	v_cvt_pk_bf16_f32 v2, v12, v13
	v_cvt_pk_bf16_f32 v3, v14, v15
	global_store_dwordx4 v[4:5], v[0:3], off offset:16
	s_waitcnt lgkmcnt(0)
	v_lshlrev_b32_e32 v8, 16, v240
	v_lshlrev_b32_e32 v9, 16, v241
	v_lshlrev_b32_e32 v10, 16, v242
	v_lshlrev_b32_e32 v11, 16, v243
	v_lshlrev_b32_e32 v12, 16, v244
	v_lshlrev_b32_e32 v13, 16, v245
	v_lshlrev_b32_e32 v14, 16, v246
	v_lshlrev_b32_e32 v15, 16, v247
	v_pk_mul_f32 v[8:9], v[248:249], v[8:9]
	v_pk_mul_f32 v[10:11], v[250:251], v[10:11]
	v_pk_mul_f32 v[12:13], v[20:21], v[12:13]
	v_pk_mul_f32 v[14:15], v[22:23], v[14:15]
	ds_read_u16 v240, v173 offset:5984
	ds_read_u16 v241, v172 offset:6800
	ds_read_u16 v242, v173 offset:6528
	ds_read_u16 v243, v172 offset:7344
	ds_read_u16 v244, v173 offset:7072
	ds_read_u16 v245, v172 offset:7888
	ds_read_u16 v246, v173 offset:7616
	ds_read_u16 v247, v172 offset:8432
	ds_read_b128 v[248:251], v163
	ds_read_b128 v[20:23], v164
	v_cvt_pk_bf16_f32 v0, v8, v9
	v_cvt_pk_bf16_f32 v1, v10, v11
	v_cvt_pk_bf16_f32 v2, v12, v13
	v_cvt_pk_bf16_f32 v3, v14, v15
	global_store_dwordx4 v[4:5], v[0:3], off offset:32
	s_waitcnt lgkmcnt(0)
	v_lshlrev_b32_e32 v8, 16, v240
	v_lshlrev_b32_e32 v9, 16, v241
	v_lshlrev_b32_e32 v10, 16, v242
	v_lshlrev_b32_e32 v11, 16, v243
	v_lshlrev_b32_e32 v12, 16, v244
	v_lshlrev_b32_e32 v13, 16, v245
	v_lshlrev_b32_e32 v14, 16, v246
	v_lshlrev_b32_e32 v15, 16, v247
	v_pk_mul_f32 v[8:9], v[248:249], v[8:9]
	v_pk_mul_f32 v[10:11], v[250:251], v[10:11]
	v_pk_mul_f32 v[12:13], v[20:21], v[12:13]
	v_pk_mul_f32 v[14:15], v[22:23], v[14:15]
	v_cvt_pk_bf16_f32 v0, v8, v9
	v_cvt_pk_bf16_f32 v1, v10, v11
	v_cvt_pk_bf16_f32 v2, v12, v13
	v_cvt_pk_bf16_f32 v3, v14, v15
	global_store_dwordx4 v[4:5], v[0:3], off offset:48
	s_waitcnt vmcnt(0)
	v_readfirstlane_b32 s8, v254
	s_cmpk_gt_i32 s8, 0x20ff
	s_cbranch_scc1 .LBB0_373
	s_cmpk_gt_i32 s8, 0x15ff
	s_mov_b64 s[6:7], -1
	s_cbranch_scc0 .LBB0_368
	s_add_i32 s6, s8, 0xea00
	s_and_b32 s7, s6, 0xffff
	s_mul_i32 s7, s7, 0xba2f
	s_lshr_b32 s9, s7, 16
	s_lshr_b32 s7, s7, 22
	s_mulk_i32 s7, 0x58
	s_sub_i32 s6, s6, s7
	s_and_b32 s7, s9, 0xffc0
	v_or_b32_e32 v2, s7, v121
	v_readlane_b32 s10, v238, 23
	s_lshl_b32 s6, s6, 6
	v_mul_u32_u24_e32 v80, 0x2c00, v2
	v_readlane_b32 s11, v238, 24
	s_and_b32 s6, s6, 0xffc0
	s_lshl_b32 s50, s6, 1
	v_lshl_add_u64 v[0:1], s[10:11], 0, v[80:81]
	v_lshlrev_b32_e32 v80, 2, v2
	v_lshl_add_u64 v[38:39], v[0:1], 0, s[50:51]
	v_lshl_add_u64 v[0:1], s[60:61], 0, v[80:81]
	s_lshl_b32 s50, s6, 13
	v_lshl_add_u64 v[40:41], v[0:1], 0, s[50:51]
	s_movk_i32 s6, 0x2000
	v_add_co_u32_e32 v0, vcc, s6, v40
	s_movk_i32 s6, 0x4000
	s_nop 0
	v_addc_co_u32_e32 v1, vcc, 0, v41, vcc
	global_load_dword v44, v[40:41], off nt
	global_load_dword v45, v[0:1], off nt
	v_add_co_u32_e32 v0, vcc, s6, v40
	s_movk_i32 s6, 0x6000
	s_nop 0
	v_addc_co_u32_e32 v1, vcc, 0, v41, vcc
	global_load_dword v46, v[0:1], off nt
	v_add_co_u32_e32 v0, vcc, s6, v40
	s_mov_b32 s6, 0x8000
	s_nop 0
	v_addc_co_u32_e32 v1, vcc, 0, v41, vcc
	global_load_dword v47, v[0:1], off nt
	v_add_co_u32_e32 v0, vcc, s6, v40
	s_mov_b32 s6, 0xa000
	s_nop 0
	v_addc_co_u32_e32 v1, vcc, 0, v41, vcc
	global_load_dword v48, v[0:1], off nt
	v_add_co_u32_e32 v0, vcc, s6, v40
	s_mov_b32 s6, 0xc000
	s_nop 0
	v_addc_co_u32_e32 v1, vcc, 0, v41, vcc
	global_load_dword v49, v[0:1], off nt
	v_add_co_u32_e32 v0, vcc, s6, v40
	s_mov_b32 s6, 0xe000
	s_nop 0
	v_addc_co_u32_e32 v1, vcc, 0, v41, vcc
	global_load_dword v66, v[0:1], off nt
	v_add_co_u32_e32 v0, vcc, s6, v40
	s_mov_b32 s6, 0x10000
	s_nop 0
	v_addc_co_u32_e32 v1, vcc, 0, v41, vcc
	global_load_dword v67, v[0:1], off nt
	v_add_co_u32_e32 v0, vcc, s6, v40
	s_mov_b32 s6, 0x12000
	s_nop 0
	v_addc_co_u32_e32 v1, vcc, 0, v41, vcc
	v_add_co_u32_e32 v2, vcc, s6, v40
	s_mov_b32 s6, 0x14000
	s_nop 0
	v_addc_co_u32_e32 v3, vcc, 0, v41, vcc
	global_load_dword v0, v[0:1], off nt
	s_waitcnt vmcnt(7)
	v_cvt_pk_bf16_f32 v44, v44, v45
	global_load_dword v1, v[2:3], off nt
	v_add_co_u32_e32 v2, vcc, s6, v40
	s_mov_b32 s6, 0x16000
	s_nop 0
	v_addc_co_u32_e32 v3, vcc, 0, v41, vcc
	v_add_co_u32_e32 v4, vcc, s6, v40
	s_mov_b32 s6, 0x18000
	s_nop 0
	v_addc_co_u32_e32 v5, vcc, 0, v41, vcc
	global_load_dword v2, v[2:3], off nt
	s_waitcnt vmcnt(7)
	v_cvt_pk_bf16_f32 v45, v46, v47
	global_load_dword v3, v[4:5], off nt
	v_add_co_u32_e32 v4, vcc, s6, v40
	s_mov_b32 s6, 0x1a000
	s_nop 0
	v_addc_co_u32_e32 v5, vcc, 0, v41, vcc
	v_add_co_u32_e32 v6, vcc, s6, v40
	s_mov_b32 s6, 0x1c000
	s_nop 0
	v_addc_co_u32_e32 v7, vcc, 0, v41, vcc
	global_load_dword v4, v[4:5], off nt
	s_waitcnt vmcnt(7)
	v_cvt_pk_bf16_f32 v46, v48, v49
	global_load_dword v5, v[6:7], off nt
	v_add_co_u32_e32 v6, vcc, s6, v40
	s_mov_b32 s6, 0x1e000
	s_nop 0
	v_addc_co_u32_e32 v7, vcc, 0, v41, vcc
	v_add_co_u32_e32 v8, vcc, s6, v40
	s_mov_b32 s6, 0x20000
	s_nop 0
	v_addc_co_u32_e32 v9, vcc, 0, v41, vcc
	global_load_dword v6, v[6:7], off nt
	s_waitcnt vmcnt(7)
	v_cvt_pk_bf16_f32 v47, v66, v67
	global_load_dword v7, v[8:9], off nt
	v_add_co_u32_e32 v8, vcc, s6, v40
	s_mov_b32 s6, 0x22000
	s_nop 0
	v_addc_co_u32_e32 v9, vcc, 0, v41, vcc
	v_add_co_u32_e32 v10, vcc, s6, v40
	s_mov_b32 s6, 0x24000
	s_nop 0
	v_addc_co_u32_e32 v11, vcc, 0, v41, vcc
	global_load_dword v8, v[8:9], off nt
	s_nop 0
	global_load_dword v9, v[10:11], off nt
	v_add_co_u32_e32 v10, vcc, s6, v40
	s_mov_b32 s6, 0x26000
	s_nop 0
	v_addc_co_u32_e32 v11, vcc, 0, v41, vcc
	v_add_co_u32_e32 v12, vcc, s6, v40
	s_mov_b32 s6, 0x28000
	s_nop 0
	v_addc_co_u32_e32 v13, vcc, 0, v41, vcc
	global_load_dword v10, v[10:11], off nt
	s_nop 0
	global_load_dword v11, v[12:13], off nt
	v_add_co_u32_e32 v12, vcc, s6, v40
	s_mov_b32 s6, 0x2a000
	s_nop 0
	v_addc_co_u32_e32 v13, vcc, 0, v41, vcc
	v_add_co_u32_e32 v14, vcc, s6, v40
	s_mov_b32 s6, 0x2c000
	s_nop 0
	v_addc_co_u32_e32 v15, vcc, 0, v41, vcc
	global_load_dword v12, v[12:13], off nt
	s_nop 0
	global_load_dword v13, v[14:15], off nt
	v_add_co_u32_e32 v14, vcc, s6, v40
	s_mov_b32 s6, 0x2e000
	s_nop 0
	v_addc_co_u32_e32 v15, vcc, 0, v41, vcc
	v_add_co_u32_e32 v16, vcc, s6, v40
	s_mov_b32 s6, 0x30000
	s_nop 0
	v_addc_co_u32_e32 v17, vcc, 0, v41, vcc
	global_load_dword v14, v[14:15], off nt
	s_nop 0
	global_load_dword v15, v[16:17], off nt
	v_add_co_u32_e32 v16, vcc, s6, v40
	s_mov_b32 s6, 0x32000
	s_nop 0
	v_addc_co_u32_e32 v17, vcc, 0, v41, vcc
	v_add_co_u32_e32 v18, vcc, s6, v40
	s_mov_b32 s6, 0x34000
	s_nop 0
	v_addc_co_u32_e32 v19, vcc, 0, v41, vcc
	global_load_dword v16, v[16:17], off nt
	s_nop 0
	global_load_dword v17, v[18:19], off nt
	v_add_co_u32_e32 v18, vcc, s6, v40
	s_mov_b32 s6, 0x36000
	s_nop 0
	v_addc_co_u32_e32 v19, vcc, 0, v41, vcc
	v_add_co_u32_e32 v20, vcc, s6, v40
	s_mov_b32 s6, 0x38000
	s_nop 0
	v_addc_co_u32_e32 v21, vcc, 0, v41, vcc
	global_load_dword v18, v[18:19], off nt
	s_nop 0
	global_load_dword v19, v[20:21], off nt
	v_add_co_u32_e32 v20, vcc, s6, v40
	s_mov_b32 s6, 0x3a000
	s_nop 0
	v_addc_co_u32_e32 v21, vcc, 0, v41, vcc
	v_add_co_u32_e32 v22, vcc, s6, v40
	s_mov_b32 s6, 0x3c000
	s_nop 0
	v_addc_co_u32_e32 v23, vcc, 0, v41, vcc
	global_load_dword v20, v[20:21], off nt
	s_nop 0
	global_load_dword v21, v[22:23], off nt
	v_add_co_u32_e32 v22, vcc, s6, v40
	s_mov_b32 s6, 0x3e000
	s_nop 0
	v_addc_co_u32_e32 v23, vcc, 0, v41, vcc
	v_add_co_u32_e32 v24, vcc, s6, v40
	s_mov_b32 s6, 0x40000
	s_nop 0
	v_addc_co_u32_e32 v25, vcc, 0, v41, vcc
	global_load_dword v22, v[22:23], off nt
	s_nop 0
	global_load_dword v23, v[24:25], off nt
	v_add_co_u32_e32 v24, vcc, s6, v40
	s_mov_b32 s6, 0x42000
	s_nop 0
	v_addc_co_u32_e32 v25, vcc, 0, v41, vcc
	v_add_co_u32_e32 v26, vcc, s6, v40
	s_mov_b32 s6, 0x44000
	s_nop 0
	v_addc_co_u32_e32 v27, vcc, 0, v41, vcc
	global_load_dword v24, v[24:25], off nt
	s_nop 0
	global_load_dword v25, v[26:27], off nt
	v_add_co_u32_e32 v26, vcc, s6, v40
	s_mov_b32 s6, 0x46000
	s_nop 0
	v_addc_co_u32_e32 v27, vcc, 0, v41, vcc
	v_add_co_u32_e32 v28, vcc, s6, v40
	s_mov_b32 s6, 0x48000
	s_nop 0
	v_addc_co_u32_e32 v29, vcc, 0, v41, vcc
	global_load_dword v26, v[26:27], off nt
	s_nop 0
	global_load_dword v27, v[28:29], off nt
	v_add_co_u32_e32 v28, vcc, s6, v40
	s_mov_b32 s6, 0x4a000
	s_nop 0
	v_addc_co_u32_e32 v29, vcc, 0, v41, vcc
	v_add_co_u32_e32 v30, vcc, s6, v40
	s_mov_b32 s6, 0x4c000
	s_nop 0
	v_addc_co_u32_e32 v31, vcc, 0, v41, vcc
	global_load_dword v28, v[28:29], off nt
	s_nop 0
	global_load_dword v29, v[30:31], off nt
	v_add_co_u32_e32 v30, vcc, s6, v40
	s_mov_b32 s6, 0x4e000
	s_nop 0
	v_addc_co_u32_e32 v31, vcc, 0, v41, vcc
	v_add_co_u32_e32 v32, vcc, s6, v40
	s_mov_b32 s6, 0x50000
	s_nop 0
	v_addc_co_u32_e32 v33, vcc, 0, v41, vcc
	global_load_dword v30, v[30:31], off nt
	s_nop 0
	global_load_dword v31, v[32:33], off nt
	v_add_co_u32_e32 v32, vcc, s6, v40
	s_mov_b32 s6, 0x52000
	s_nop 0
	v_addc_co_u32_e32 v33, vcc, 0, v41, vcc
	v_add_co_u32_e32 v34, vcc, s6, v40
	s_mov_b32 s6, 0x54000
	s_nop 0
	v_addc_co_u32_e32 v35, vcc, 0, v41, vcc
	global_load_dword v32, v[32:33], off nt
	s_nop 0
	global_load_dword v33, v[34:35], off nt
	v_add_co_u32_e32 v34, vcc, s6, v40
	s_mov_b32 s6, 0x56000
	s_nop 0
	v_addc_co_u32_e32 v35, vcc, 0, v41, vcc
	v_add_co_u32_e32 v36, vcc, s6, v40
	s_mov_b32 s6, 0x58000
	s_nop 0
	v_addc_co_u32_e32 v37, vcc, 0, v41, vcc
	global_load_dword v34, v[34:35], off nt
	s_nop 0
	global_load_dword v35, v[36:37], off nt
	v_add_co_u32_e32 v36, vcc, s6, v40
	s_mov_b32 s6, 0x5a000
	s_nop 0
	v_addc_co_u32_e32 v37, vcc, 0, v41, vcc
	v_add_co_u32_e32 v42, vcc, s6, v40
	s_mov_b32 s6, 0x5c000
	s_nop 0
	v_addc_co_u32_e32 v43, vcc, 0, v41, vcc
	global_load_dword v36, v[36:37], off nt
	s_nop 0
	global_load_dword v37, v[42:43], off nt
	v_add_co_u32_e32 v42, vcc, s6, v40
	s_mov_b32 s6, 0x5e000
	s_nop 0
	v_addc_co_u32_e32 v43, vcc, 0, v41, vcc
	v_add_co_u32_e32 v50, vcc, s6, v40
	s_mov_b32 s6, 0x60000
	s_nop 0
	v_addc_co_u32_e32 v51, vcc, 0, v41, vcc
	global_load_dword v42, v[42:43], off nt
	s_nop 0
	global_load_dword v43, v[50:51], off nt
	v_add_co_u32_e32 v50, vcc, s6, v40
	s_mov_b32 s6, 0x62000
	s_nop 0
	v_addc_co_u32_e32 v51, vcc, 0, v41, vcc
	v_add_co_u32_e32 v52, vcc, s6, v40
	s_mov_b32 s6, 0x64000
	s_nop 0
	v_addc_co_u32_e32 v53, vcc, 0, v41, vcc
	global_load_dword v50, v[50:51], off nt
	s_nop 0
	global_load_dword v51, v[52:53], off nt
	v_add_co_u32_e32 v52, vcc, s6, v40
	s_mov_b32 s6, 0x66000
	s_nop 0
	v_addc_co_u32_e32 v53, vcc, 0, v41, vcc
	v_add_co_u32_e32 v54, vcc, s6, v40
	s_mov_b32 s6, 0x68000
	s_nop 0
	v_addc_co_u32_e32 v55, vcc, 0, v41, vcc
	global_load_dword v52, v[52:53], off nt
	s_nop 0
	global_load_dword v53, v[54:55], off nt
	v_add_co_u32_e32 v54, vcc, s6, v40
	s_mov_b32 s6, 0x6a000
	s_nop 0
	v_addc_co_u32_e32 v55, vcc, 0, v41, vcc
	v_add_co_u32_e32 v56, vcc, s6, v40
	s_mov_b32 s6, 0x6c000
	s_nop 0
	v_addc_co_u32_e32 v57, vcc, 0, v41, vcc
	global_load_dword v54, v[54:55], off nt
	s_nop 0
	global_load_dword v55, v[56:57], off nt
	v_add_co_u32_e32 v56, vcc, s6, v40
	s_mov_b32 s6, 0x6e000
	s_nop 0
	v_addc_co_u32_e32 v57, vcc, 0, v41, vcc
	v_add_co_u32_e32 v58, vcc, s6, v40
	s_mov_b32 s6, 0x70000
	s_nop 0
	v_addc_co_u32_e32 v59, vcc, 0, v41, vcc
	global_load_dword v56, v[56:57], off nt
	s_nop 0
	global_load_dword v57, v[58:59], off nt
	v_add_co_u32_e32 v58, vcc, s6, v40
	s_mov_b32 s6, 0x72000
	s_nop 0
	v_addc_co_u32_e32 v59, vcc, 0, v41, vcc
	v_add_co_u32_e32 v60, vcc, s6, v40
	s_mov_b32 s6, 0x74000
	s_nop 0
	v_addc_co_u32_e32 v61, vcc, 0, v41, vcc
	global_load_dword v58, v[58:59], off nt
	s_nop 0
	global_load_dword v59, v[60:61], off nt
	v_add_co_u32_e32 v60, vcc, s6, v40
	s_mov_b32 s6, 0x76000
	s_nop 0
	v_addc_co_u32_e32 v61, vcc, 0, v41, vcc
	v_add_co_u32_e32 v62, vcc, s6, v40
	s_mov_b32 s6, 0x78000
	s_nop 0
	v_addc_co_u32_e32 v63, vcc, 0, v41, vcc
	global_load_dword v60, v[60:61], off nt
	s_nop 0
	global_load_dword v61, v[62:63], off nt
	v_add_co_u32_e32 v62, vcc, s6, v40
	s_mov_b32 s6, 0x7a000
	s_nop 0
	v_addc_co_u32_e32 v63, vcc, 0, v41, vcc
	v_add_co_u32_e32 v64, vcc, s6, v40
	s_mov_b32 s6, 0x7c000
	s_nop 0
	v_addc_co_u32_e32 v65, vcc, 0, v41, vcc
	global_load_dword v62, v[62:63], off nt
	s_nop 0
	global_load_dword v63, v[64:65], off nt
	v_add_co_u32_e32 v64, vcc, s6, v40
	s_mov_b32 s6, 0x7e000
	s_nop 0
	v_addc_co_u32_e32 v65, vcc, 0, v41, vcc
	v_add_co_u32_e32 v40, vcc, s6, v40
	global_load_dword v64, v[64:65], off nt
	s_nop 0
	v_addc_co_u32_e32 v41, vcc, 0, v41, vcc
	global_load_dword v65, v[40:41], off nt
	s_mov_b64 s[6:7], 0
	global_store_dwordx4 v[38:39], v[44:47], off

.LBB0_441:
	v_and_b32_e32 v18, 15, v176
	v_bfe_u32 v19, v176, 4, 2
	v_mul_u32_u24_e32 v36, 0x110, v19
	v_lshl_add_u32 v36, v18, 2, v36
	v_add_u32_e32 v36, s14, v36
	v_mul_u32_u24_e32 v37, 0x1d0, v19
	v_add_u32_e32 v37, v132, v37
	s_mul_i32 s10, s11, 0x2100
	v_lshl_add_u32 v18, v19, 11, v132
	v_add_u32_e32 v18, s10, v18
	ds_read_b32 v240, v36
	ds_read_b32 v241, v37
	ds_read_b32 v242, v37 offset:64
	ds_read_b32 v243, v37 offset:128
	ds_read_b32 v244, v37 offset:192
	ds_read_b32 v245, v36 offset:1088
	ds_read_b32 v246, v37 offset:2112
	ds_read_b32 v247, v37 offset:2176
	ds_read_b32 v248, v37 offset:2240
	ds_read_b32 v249, v37 offset:2304
	ds_read_b32 v250, v36 offset:2176
	ds_read_b32 v251, v37 offset:4224
	ds_read_b32 v252, v37 offset:4288
	ds_read_b32 v253, v37 offset:4352
	ds_read_b32 v254, v37 offset:4416
	s_waitcnt lgkmcnt(10)
	v_mfma_f32_16x16x4_f32 v[20:23], v240, v241, 0
	v_mfma_f32_16x16x4_f32 v[24:27], v240, v242, 0
	v_mfma_f32_16x16x4_f32 v[28:31], v240, v243, 0
	v_mfma_f32_16x16x4_f32 v[32:35], v240, v244, 0
	ds_read_b32 v240, v36 offset:3264
	ds_read_b32 v241, v37 offset:6336
	ds_read_b32 v242, v37 offset:6400
	ds_read_b32 v243, v37 offset:6464
	ds_read_b32 v244, v37 offset:6528
	s_waitcnt lgkmcnt(10)
	v_mfma_f32_16x16x4_f32 v[20:23], v245, v246, v[20:23]
	v_mfma_f32_16x16x4_f32 v[24:27], v245, v247, v[24:27]
	v_mfma_f32_16x16x4_f32 v[28:31], v245, v248, v[28:31]
	v_mfma_f32_16x16x4_f32 v[32:35], v245, v249, v[32:35]
	ds_read_b32 v245, v36 offset:4352
	ds_read_b32 v246, v37 offset:8448
	ds_read_b32 v247, v37 offset:8512
	ds_read_b32 v248, v37 offset:8576
	ds_read_b32 v249, v37 offset:8640
	s_waitcnt lgkmcnt(10)
	v_mfma_f32_16x16x4_f32 v[20:23], v250, v251, v[20:23]
	v_mfma_f32_16x16x4_f32 v[24:27], v250, v252, v[24:27]
	v_mfma_f32_16x16x4_f32 v[28:31], v250, v253, v[28:31]
	v_mfma_f32_16x16x4_f32 v[32:35], v250, v254, v[32:35]
	ds_read_b32 v250, v36 offset:5440
	ds_read_b32 v251, v37 offset:10560
	ds_read_b32 v252, v37 offset:10624
	ds_read_b32 v253, v37 offset:10688
	ds_read_b32 v254, v37 offset:10752
	s_waitcnt lgkmcnt(10)
	v_mfma_f32_16x16x4_f32 v[20:23], v240, v241, v[20:23]
	v_mfma_f32_16x16x4_f32 v[24:27], v240, v242, v[24:27]
	v_mfma_f32_16x16x4_f32 v[28:31], v240, v243, v[28:31]
	v_mfma_f32_16x16x4_f32 v[32:35], v240, v244, v[32:35]
	ds_read_b32 v240, v36 offset:6528
	ds_read_b32 v241, v37 offset:12672
	ds_read_b32 v242, v37 offset:12736
	ds_read_b32 v243, v37 offset:12800
	ds_read_b32 v244, v37 offset:12864
	s_cmp_eq_u32 s11, 1
	s_cbranch_scc1 .Lsm_done
	s_waitcnt lgkmcnt(10)
	v_mfma_f32_16x16x4_f32 v[20:23], v245, v246, v[20:23]
	v_mfma_f32_16x16x4_f32 v[24:27], v245, v247, v[24:27]
	v_mfma_f32_16x16x4_f32 v[28:31], v245, v248, v[28:31]
	v_mfma_f32_16x16x4_f32 v[32:35], v245, v249, v[32:35]
	ds_read_b32 v245, v36 offset:7616
	ds_read_b32 v246, v37 offset:14784
	ds_read_b32 v247, v37 offset:14848
	ds_read_b32 v248, v37 offset:14912
	ds_read_b32 v249, v37 offset:14976
	s_waitcnt lgkmcnt(10)
	v_mfma_f32_16x16x4_f32 v[20:23], v250, v251, v[20:23]
	v_mfma_f32_16x16x4_f32 v[24:27], v250, v252, v[24:27]
	v_mfma_f32_16x16x4_f32 v[28:31], v250, v253, v[28:31]
	v_mfma_f32_16x16x4_f32 v[32:35], v250, v254, v[32:35]
	ds_read_b32 v250, v36 offset:8704
	ds_read_b32 v251, v37 offset:16896
	ds_read_b32 v252, v37 offset:16960
	ds_read_b32 v253, v37 offset:17024
	ds_read_b32 v254, v37 offset:17088
	s_waitcnt lgkmcnt(10)
	v_mfma_f32_16x16x4_f32 v[20:23], v240, v241, v[20:23]
	v_mfma_f32_16x16x4_f32 v[24:27], v240, v242, v[24:27]
	v_mfma_f32_16x16x4_f32 v[28:31], v240, v243, v[28:31]
	v_mfma_f32_16x16x4_f32 v[32:35], v240, v244, v[32:35]
	ds_read_b32 v240, v36 offset:9792
	ds_read_b32 v241, v37 offset:19008
	ds_read_b32 v242, v37 offset:19072
	ds_read_b32 v243, v37 offset:19136
	ds_read_b32 v244, v37 offset:19200
	s_waitcnt lgkmcnt(10)
	v_mfma_f32_16x16x4_f32 v[20:23], v245, v246, v[20:23]
	v_mfma_f32_16x16x4_f32 v[24:27], v245, v247, v[24:27]
	v_mfma_f32_16x16x4_f32 v[28:31], v245, v248, v[28:31]
	v_mfma_f32_16x16x4_f32 v[32:35], v245, v249, v[32:35]
	ds_read_b32 v245, v36 offset:10880
	ds_read_b32 v246, v37 offset:21120
	ds_read_b32 v247, v37 offset:21184
	ds_read_b32 v248, v37 offset:21248
	ds_read_b32 v249, v37 offset:21312
	s_cmp_eq_u32 s11, 2
	s_cbranch_scc1 .Lsm_done
	s_waitcnt lgkmcnt(10)
	v_mfma_f32_16x16x4_f32 v[20:23], v250, v251, v[20:23]
	v_mfma_f32_16x16x4_f32 v[24:27], v250, v252, v[24:27]
	v_mfma_f32_16x16x4_f32 v[28:31], v250, v253, v[28:31]
	v_mfma_f32_16x16x4_f32 v[32:35], v250, v254, v[32:35]
	ds_read_b32 v250, v36 offset:11968
	ds_read_b32 v251, v37 offset:23232
	ds_read_b32 v252, v37 offset:23296
	ds_read_b32 v253, v37 offset:23360
	ds_read_b32 v254, v37 offset:23424
	s_waitcnt lgkmcnt(10)
	v_mfma_f32_16x16x4_f32 v[20:23], v240, v241, v[20:23]
	v_mfma_f32_16x16x4_f32 v[24:27], v240, v242, v[24:27]
	v_mfma_f32_16x16x4_f32 v[28:31], v240, v243, v[28:31]
	v_mfma_f32_16x16x4_f32 v[32:35], v240, v244, v[32:35]
	ds_read_b32 v240, v36 offset:13056
	ds_read_b32 v241, v37 offset:25344
	ds_read_b32 v242, v37 offset:25408
	ds_read_b32 v243, v37 offset:25472
	ds_read_b32 v244, v37 offset:25536
	s_waitcnt lgkmcnt(10)
	v_mfma_f32_16x16x4_f32 v[20:23], v245, v246, v[20:23]
	v_mfma_f32_16x16x4_f32 v[24:27], v245, v247, v[24:27]
	v_mfma_f32_16x16x4_f32 v[28:31], v245, v248, v[28:31]
	v_mfma_f32_16x16x4_f32 v[32:35], v245, v249, v[32:35]
	ds_read_b32 v245, v36 offset:14144
	ds_read_b32 v246, v37 offset:27456
	ds_read_b32 v247, v37 offset:27520
	ds_read_b32 v248, v37 offset:27584
	ds_read_b32 v249, v37 offset:27648
	s_waitcnt lgkmcnt(10)
	v_mfma_f32_16x16x4_f32 v[20:23], v250, v251, v[20:23]
	v_mfma_f32_16x16x4_f32 v[24:27], v250, v252, v[24:27]
	v_mfma_f32_16x16x4_f32 v[28:31], v250, v253, v[28:31]
	v_mfma_f32_16x16x4_f32 v[32:35], v250, v254, v[32:35]
	ds_read_b32 v250, v36 offset:15232
	ds_read_b32 v251, v37 offset:29568
	ds_read_b32 v252, v37 offset:29632
	ds_read_b32 v253, v37 offset:29696
	ds_read_b32 v254, v37 offset:29760
.Lsm_done:
	s_waitcnt lgkmcnt(0)
	s_nop 7
	s_nop 3
	ds_write_b32 v18, v20
	ds_write_b32 v18, v21 offset:528
	ds_write_b32 v18, v22 offset:1056
	ds_write_b32 v18, v23 offset:1584
	ds_write_b32 v18, v24 offset:64
	ds_write_b32 v18, v25 offset:592
	ds_write_b32 v18, v26 offset:1120
	ds_write_b32 v18, v27 offset:1648
	ds_write_b32 v18, v28 offset:128
	ds_write_b32 v18, v29 offset:656
	ds_write_b32 v18, v30 offset:1184
	ds_write_b32 v18, v31 offset:1712
	ds_write_b32 v18, v32 offset:192
	ds_write_b32 v18, v33 offset:720
	ds_write_b32 v18, v34 offset:1248
	ds_write_b32 v18, v35 offset:1776
	v_add_u32_e32 v19, s10, v132
	s_waitcnt lgkmcnt(0)
	ds_read_b32 v240, v19
	ds_read_b32 v241, v19 offset:528
	ds_read_b32 v242, v19 offset:1056
	ds_read_b32 v243, v19 offset:1584
	ds_read_b32 v244, v19 offset:2112
	ds_read_b32 v245, v19 offset:2640
	ds_read_b32 v246, v19 offset:3168
	ds_read_b32 v247, v19 offset:3696
	ds_read_b32 v248, v19 offset:4224
	ds_read_b32 v249, v19 offset:4752
	ds_read_b32 v250, v19 offset:5280
	ds_read_b32 v251, v19 offset:5808
	ds_read_b32 v252, v19 offset:6336
	ds_read_b32 v253, v19 offset:6864
	ds_read_b32 v254, v19 offset:7392
	ds_read_b32 v255, v19 offset:7920
	s_waitcnt lgkmcnt(0)
	v_sub_f32_e32 v0, v0, v240
	v_sub_f32_e32 v1, v1, v241
	v_sub_f32_e32 v2, v2, v242
	v_sub_f32_e32 v3, v3, v243
	v_sub_f32_e32 v4, v4, v244
	v_sub_f32_e32 v5, v5, v245
	v_sub_f32_e32 v6, v6, v246
	v_sub_f32_e32 v7, v7, v247
	v_sub_f32_e32 v8, v8, v248
	v_sub_f32_e32 v9, v9, v249
	v_sub_f32_e32 v10, v10, v250
	v_sub_f32_e32 v11, v11, v251
	v_sub_f32_e32 v12, v12, v252
	v_sub_f32_e32 v13, v13, v253
	v_sub_f32_e32 v14, v14, v254
	v_sub_f32_e32 v15, v15, v255
	s_max_u32 s10, s33, 1
	s_bitcmp0_b32 s10, 0
	s_cbranch_scc1 .LBB0_375
	s_and_b32 s7, s7, 1
	s_mulk_i32 s7, 0x210
	s_mov_b32 s10, 0
